# nt (streaming) hint on the K/V row loads of the shared sample-step attention tasks (window-0 and memory cache), which are read once
# speedup vs baseline: 1.0347x; 1.0049x over previous
.LBB0_768:
	s_and_b64 vcc, exec, s[0:1]
	s_cbranch_vccz .LBB0_1040
	s_mov_b64 s[40:41], s[38:39]
	s_mov_b64 s[0:1], s[36:37]
	v_mov_b32_e32 v113, v192
	s_add_i32 s96, s57, -6
	v_ashrrev_i32_e32 v115, 6, v113
	v_bfe_u32 v119, v113, 4, 2
	v_lshl_or_b32 v129, v115, 5, v119
	s_lshl_b32 s4, s44, 19
	s_lshl_b64 s[0:1], s[96:97], 8
	v_min_i32_e32 v110, 0xff, v129
	v_and_b32_e32 v117, 15, v113
	s_add_u32 s6, s86, s0
	v_ashrrev_i32_e32 v111, 31, v110
	s_addc_u32 s7, s87, s1
	v_lshlrev_b32_e32 v136, 4, v117
	s_waitcnt lgkmcnt(0)
	v_lshlrev_b64 v[2:3], 11, v[110:111]
	s_mov_b32 s5, s97
	v_or_b32_e32 v111, 4, v129
	v_lshl_add_u64 v[0:1], s[6:7], 0, v[136:137]
	v_lshl_add_u64 v[2:3], v[2:3], 0, s[4:5]
	v_min_i32_e32 v108, 0xff, v111
	v_lshl_add_u64 v[4:5], v[0:1], 0, v[2:3]
	v_ashrrev_i32_e32 v109, 31, v108
	global_load_dwordx4 v[88:91], v[4:5], off nt
	v_lshlrev_b64 v[4:5], 11, v[108:109]
	v_or_b32_e32 v109, 8, v129
	v_min_i32_e32 v106, 0xff, v109
	s_lshl_b32 s96, s96, 6
	v_ashrrev_i32_e32 v107, 31, v106
	s_lshl_b32 s6, s44, 13
	s_lshl_b64 s[8:9], s[96:97], 2
	v_lshlrev_b64 v[8:9], 11, v[106:107]
	v_or_b32_e32 v107, 12, v129
	s_add_u32 s8, s40, s8
	v_min_i32_e32 v104, 0xff, v107
	s_addc_u32 s9, s41, s9
	v_ashrrev_i32_e32 v105, 31, v104
	v_lshl_add_u64 v[16:17], s[8:9], 0, v[136:137]
	s_mov_b32 s7, s97
	v_lshlrev_b64 v[12:13], 11, v[104:105]
	v_or_b32_e32 v105, 16, v129
	v_lshl_add_u64 v[16:17], v[16:17], 0, s[6:7]
	s_mov_b32 s6, 0x8e8d000
	v_add_co_u32_e32 v18, vcc, s6, v16
	v_min_i32_e32 v102, 0xff, v105
	s_mov_b64 s[6:7], 0x8e8da00
	v_addc_co_u32_e32 v19, vcc, 0, v17, vcc
	v_ashrrev_i32_e32 v103, 31, v102
	v_lshl_add_u64 v[22:23], v[16:17], 0, s[6:7]
	flat_load_dwordx4 v[64:67], v[18:19] offset:2560 nt
	flat_load_dwordx4 v[60:63], v[22:23] offset:1024 nt
	v_lshlrev_b64 v[18:19], 11, v[102:103]
	v_or_b32_e32 v103, 20, v129
	v_min_i32_e32 v100, 0xff, v103
	v_ashrrev_i32_e32 v101, 31, v100
	v_lshlrev_b64 v[24:25], 11, v[100:101]
	v_or_b32_e32 v101, 24, v129
	v_min_i32_e32 v98, 0xff, v101
	v_ashrrev_i32_e32 v99, 31, v98
	flat_load_dwordx4 v[56:59], v[22:23] offset:2048 nt
	flat_load_dwordx4 v[52:55], v[22:23] offset:3072 nt
	v_lshlrev_b64 v[22:23], 11, v[98:99]
	v_lshl_add_u64 v[22:23], v[22:23], 0, s[4:5]
	v_or_b32_e32 v99, 28, v129
	v_lshl_add_u64 v[28:29], v[0:1], 0, v[22:23]
	v_lshl_add_u64 v[22:23], s[86:87], 0, v[22:23]
	v_min_i32_e32 v96, 0xff, v99
	s_mov_b32 s6, 0x8e8e000
	v_lshl_add_u64 v[22:23], v[22:23], 0, s[0:1]
	v_ashrrev_i32_e32 v97, 31, v96
	v_add_co_u32_e32 v30, vcc, s6, v16
	v_lshl_add_u64 v[48:49], v[22:23], 0, v[136:137]
	v_lshlrev_b64 v[22:23], 11, v[96:97]
	v_lshl_add_u64 v[4:5], v[4:5], 0, s[4:5]
	v_lshl_add_u64 v[8:9], v[8:9], 0, s[4:5]
	v_lshl_add_u64 v[12:13], v[12:13], 0, s[4:5]
	v_lshl_add_u64 v[18:19], v[18:19], 0, s[4:5]
	v_lshl_add_u64 v[24:25], v[24:25], 0, s[4:5]
	v_addc_co_u32_e32 v31, vcc, 0, v17, vcc
	v_lshl_add_u64 v[22:23], v[22:23], 0, s[4:5]
	s_mov_b32 s4, 0x8e8f000
	v_add_co_u32_e32 v16, vcc, s4, v16
	flat_load_dwordx4 v[44:47], v[30:31] offset:2560 nt
	s_nop 0
	v_addc_co_u32_e32 v17, vcc, 0, v17, vcc
	flat_load_dwordx4 v[40:43], v[30:31] offset:3584 nt
	flat_load_dwordx4 v[36:39], v[16:17] offset:512 nt
	v_lshl_add_u64 v[2:3], s[86:87], 0, v[2:3]
	v_lshl_add_u64 v[6:7], v[0:1], 0, v[4:5]
	v_lshl_add_u64 v[4:5], s[86:87], 0, v[4:5]
	v_lshl_add_u64 v[10:11], v[0:1], 0, v[8:9]
	v_lshl_add_u64 v[8:9], s[86:87], 0, v[8:9]
	v_lshl_add_u64 v[14:15], v[0:1], 0, v[12:13]
	v_lshl_add_u64 v[12:13], s[86:87], 0, v[12:13]
	v_lshl_add_u64 v[20:21], v[0:1], 0, v[18:19]
	v_lshl_add_u64 v[18:19], s[86:87], 0, v[18:19]
	v_lshl_add_u64 v[26:27], v[0:1], 0, v[24:25]
	v_lshl_add_u64 v[24:25], s[86:87], 0, v[24:25]
	v_lshl_add_u64 v[2:3], v[2:3], 0, s[0:1]
	v_lshl_add_u64 v[4:5], v[4:5], 0, s[0:1]
	v_lshl_add_u64 v[8:9], v[8:9], 0, s[0:1]
	v_lshl_add_u64 v[12:13], v[12:13], 0, s[0:1]
	v_lshl_add_u64 v[18:19], v[18:19], 0, s[0:1]
	v_lshl_add_u64 v[24:25], v[24:25], 0, s[0:1]
	v_lshl_add_u64 v[30:31], v[0:1], 0, v[22:23]
	v_lshl_add_u64 v[0:1], s[86:87], 0, v[22:23]
	v_lshl_add_u64 v[2:3], v[2:3], 0, v[136:137]
	v_lshl_add_u64 v[4:5], v[4:5], 0, v[136:137]
	v_lshl_add_u64 v[8:9], v[8:9], 0, v[136:137]
	v_lshl_add_u64 v[12:13], v[12:13], 0, v[136:137]
	v_lshl_add_u64 v[18:19], v[18:19], 0, v[136:137]
	v_lshl_add_u64 v[24:25], v[24:25], 0, v[136:137]
	v_lshl_add_u64 v[0:1], v[0:1], 0, s[0:1]
	v_lshl_add_u64 v[120:121], v[0:1], 0, v[136:137]
	global_load_dwordx4 v[0:3], v[2:3], off offset:1024 nt
	s_nop 0
	global_load_dwordx4 v[92:95], v[6:7], off nt
	s_nop 0
	global_load_dwordx4 v[4:7], v[4:5], off offset:1024 nt
	s_nop 0
	global_load_dwordx4 v[84:87], v[10:11], off nt
	s_nop 0
	global_load_dwordx4 v[8:11], v[8:9], off offset:1024 nt
	s_nop 0
	flat_load_dwordx4 v[32:35], v[16:17] offset:1536 nt
	global_load_dwordx4 v[80:83], v[14:15], off nt
	s_nop 0
	global_load_dwordx4 v[12:15], v[12:13], off offset:1024 nt
	s_nop 0
	global_load_dwordx4 v[76:79], v[20:21], off nt
	s_nop 0
	global_load_dwordx4 v[16:19], v[18:19], off offset:1024 nt
	s_nop 0
	global_load_dwordx4 v[72:75], v[26:27], off nt
	global_load_dwordx4 v[20:23], v[24:25], off offset:1024 nt
	global_load_dwordx4 v[68:71], v[28:29], off nt
	s_nop 0
	global_load_dwordx4 v[24:27], v[48:49], off offset:1024 nt
	s_nop 0
	global_load_dwordx4 v[48:51], v[30:31], off nt
	s_nop 0
	global_load_dwordx4 v[28:31], v[120:121], off offset:1024 nt
	v_and_b32_e32 v97, 7, v113
	v_cmp_eq_u32_e32 vcc, 7, v97
	v_cmp_eq_u32_e64 s[18:19], 6, v97
	v_cmp_eq_u32_e64 s[20:21], 5, v97
	v_cmp_eq_u32_e64 s[22:23], 4, v97
	v_cmp_eq_u32_e64 s[24:25], 3, v97
	v_cmp_eq_u32_e64 s[26:27], 2, v97
	v_cmp_eq_u32_e64 s[28:29], 1, v97
	s_movk_i32 s0, 0x420
	v_mad_u32_u24 v130, v117, s0, 16
	s_movk_i32 s0, 0x100
	s_waitcnt vmcnt(0) lgkmcnt(0)
	v_mul_f32_e32 v97, v89, v65
	v_mul_f32_e32 v114, v89, v61
	v_fmac_f32_e32 v97, v88, v64
	v_fmac_f32_e32 v114, v88, v60
	v_fmac_f32_e32 v97, v90, v66
	v_fmac_f32_e32 v114, v90, v62
	v_fmac_f32_e32 v97, v91, v67
	v_fmac_f32_e32 v114, v91, v63
	v_cmp_gt_u32_e64 s[30:31], 8, v117
	v_add_f32_dpp v97, v97, v97 quad_perm:[1,0,3,2] row_mask:0xf bank_mask:0xf bound_ctrl:1
	v_mul_f32_e32 v118, v89, v57
	v_mul_f32_e32 v121, v89, v53
	v_fmac_f32_e32 v118, v88, v56
	v_fmac_f32_e32 v121, v88, v52
	v_fmac_f32_e32 v118, v90, v58
	v_fmac_f32_e32 v121, v90, v54
	v_fmac_f32_e32 v118, v91, v59
	v_fmac_f32_e32 v121, v91, v55
	v_add_f32_dpp v114, v114, v114 quad_perm:[1,0,3,2] row_mask:0xf bank_mask:0xf bound_ctrl:1
	v_add_f32_dpp v118, v118, v118 quad_perm:[1,0,3,2] row_mask:0xf bank_mask:0xf bound_ctrl:1
	v_add_f32_dpp v121, v121, v121 quad_perm:[1,0,3,2] row_mask:0xf bank_mask:0xf bound_ctrl:1
	v_add_f32_dpp v97, v97, v97 quad_perm:[2,3,0,1] row_mask:0xf bank_mask:0xf bound_ctrl:1
	v_add_f32_dpp v114, v114, v114 quad_perm:[2,3,0,1] row_mask:0xf bank_mask:0xf bound_ctrl:1
	v_add_f32_dpp v118, v118, v118 quad_perm:[2,3,0,1] row_mask:0xf bank_mask:0xf bound_ctrl:1
	v_add_f32_dpp v121, v121, v121 quad_perm:[2,3,0,1] row_mask:0xf bank_mask:0xf bound_ctrl:1
	v_add_f32_dpp v97, v97, v97 row_ror:4 row_mask:0xf bank_mask:0xf bound_ctrl:1
	v_add_f32_dpp v114, v114, v114 row_ror:4 row_mask:0xf bank_mask:0xf bound_ctrl:1
	v_add_f32_dpp v118, v118, v118 row_ror:4 row_mask:0xf bank_mask:0xf bound_ctrl:1
	v_add_f32_dpp v121, v121, v121 row_ror:4 row_mask:0xf bank_mask:0xf bound_ctrl:1
	v_cmp_gt_i32_e64 s[0:1], s0, v129
	v_mov_b32_dpp v112, v97 row_ror:8 row_mask:0xf bank_mask:0xf bound_ctrl:1
	v_mov_b32_dpp v116, v114 row_ror:8 row_mask:0xf bank_mask:0xf bound_ctrl:1
	v_mov_b32_dpp v120, v118 row_ror:8 row_mask:0xf bank_mask:0xf bound_ctrl:1
	v_mov_b32_dpp v122, v121 row_ror:8 row_mask:0xf bank_mask:0xf bound_ctrl:1
	s_and_b64 s[6:7], s[30:31], s[0:1]
	v_mul_f32_e32 v123, v89, v45
	v_fmac_f32_e32 v123, v88, v44
	v_fmac_f32_e32 v123, v90, v46
	v_mul_f32_e32 v125, v89, v41
	v_mul_f32_e32 v127, v89, v37
	v_fmac_f32_e32 v125, v88, v40
	v_fmac_f32_e32 v127, v88, v36
	v_fmac_f32_e32 v125, v90, v42
	v_fmac_f32_e32 v127, v90, v38
	v_fmac_f32_e32 v123, v91, v47
	v_fmac_f32_e32 v125, v91, v43
	v_fmac_f32_e32 v127, v91, v39
	v_add_f32_dpp v123, v123, v123 quad_perm:[1,0,3,2] row_mask:0xf bank_mask:0xf bound_ctrl:1
	v_add_f32_dpp v125, v125, v125 quad_perm:[1,0,3,2] row_mask:0xf bank_mask:0xf bound_ctrl:1
	v_add_f32_dpp v127, v127, v127 quad_perm:[1,0,3,2] row_mask:0xf bank_mask:0xf bound_ctrl:1
	v_add_f32_dpp v123, v123, v123 quad_perm:[2,3,0,1] row_mask:0xf bank_mask:0xf bound_ctrl:1
	v_add_f32_dpp v125, v125, v125 quad_perm:[2,3,0,1] row_mask:0xf bank_mask:0xf bound_ctrl:1
	v_add_f32_dpp v127, v127, v127 quad_perm:[2,3,0,1] row_mask:0xf bank_mask:0xf bound_ctrl:1
	v_add_f32_dpp v123, v123, v123 row_ror:4 row_mask:0xf bank_mask:0xf bound_ctrl:1
	v_add_f32_dpp v125, v125, v125 row_ror:4 row_mask:0xf bank_mask:0xf bound_ctrl:1
	v_add_f32_dpp v127, v127, v127 row_ror:4 row_mask:0xf bank_mask:0xf bound_ctrl:1
	v_mov_b32_dpp v124, v123 row_ror:8 row_mask:0xf bank_mask:0xf bound_ctrl:1
	v_mul_f32_e32 v89, v89, v33
	v_fmac_f32_e32 v89, v88, v32
	v_fmac_f32_e32 v89, v90, v34
	v_fmac_f32_e32 v89, v91, v35
	v_mov_b32_dpp v126, v125 row_ror:8 row_mask:0xf bank_mask:0xf bound_ctrl:1
	v_mov_b32_dpp v128, v127 row_ror:8 row_mask:0xf bank_mask:0xf bound_ctrl:1
	v_add_f32_dpp v88, v89, v89 quad_perm:[1,0,3,2] row_mask:0xf bank_mask:0xf bound_ctrl:1
	s_barrier
	s_nop 0
	v_add_f32_dpp v88, v88, v88 quad_perm:[2,3,0,1] row_mask:0xf bank_mask:0xf bound_ctrl:1
	s_nop 1
	v_add_f32_dpp v89, v88, v88 row_ror:4 row_mask:0xf bank_mask:0xf bound_ctrl:1
	v_lshl_add_u32 v88, v129, 2, v130
	s_nop 0
	v_mov_b32_dpp v90, v89 row_ror:8 row_mask:0xf bank_mask:0xf bound_ctrl:1
	s_and_saveexec_b64 s[4:5], s[6:7]
	s_cbranch_execz .LBB0_771
	v_add_f32_e32 v114, v114, v116
	v_add_f32_e32 v97, v97, v112
	v_add_f32_e32 v118, v118, v120
	v_cndmask_b32_e64 v97, v97, v114, s[28:29]
	v_add_f32_e32 v121, v121, v122
	v_cndmask_b32_e64 v97, v97, v118, s[26:27]
	v_add_f32_e32 v123, v123, v124
	v_cndmask_b32_e64 v97, v97, v121, s[24:25]
	v_add_f32_e32 v91, v125, v126
	v_cndmask_b32_e64 v97, v97, v123, s[22:23]
	v_add_f32_e32 v89, v89, v90
	v_add_f32_e32 v90, v127, v128
	v_cndmask_b32_e64 v91, v97, v91, s[20:21]
	v_cndmask_b32_e64 v90, v91, v90, s[18:19]
	v_cndmask_b32_e32 v89, v90, v89, vcc
	ds_write_b32 v88, v89

.LBB0_921:
	s_mov_b64 s[28:29], s[38:39]
	s_mov_b64 s[0:1], s[36:37]
	v_mov_b32_e32 v71, v192
	s_add_u32 s4, s0, 0x4a40000
	v_ashrrev_i32_e32 v69, 6, v71
	v_bfe_u32 v75, v71, 4, 2
	v_lshl_add_u32 v70, v69, 4, v69
	v_add_u32_e32 v76, v75, v70
	v_min_i32_e32 v68, 0x87, v76
	s_addc_u32 s5, s1, 0
	v_add_u32_e32 v0, -8, v68
	v_ashrrev_i32_e32 v1, 31, v68
	v_cmp_gt_i32_e32 vcc, s48, v76
	v_mov_b32_e32 v10, s5
	v_mov_b32_e32 v11, s81
	v_cndmask_b32_e32 v1, 0, v1, vcc
	v_cndmask_b32_e32 v0, v0, v68, vcc
	v_mov_b32_e32 v12, s4
	v_mov_b32_e32 v13, s80
	s_waitcnt lgkmcnt(0)
	v_cndmask_b32_e32 v3, v10, v11, vcc
	v_cndmask_b32_e32 v2, v12, v13, vcc
	v_lshlrev_b64 v[0:1], 10, v[0:1]
	v_lshl_add_u64 v[0:1], v[2:3], 0, v[0:1]
	v_min_i32_e32 v2, 0x83, v76
	v_add_u32_e32 v4, 4, v2
	s_movk_i32 s4, 0x7c
	v_add_u32_e32 v2, -4, v2
	v_ashrrev_i32_e32 v3, 31, v4
	v_cmp_gt_i32_e32 vcc, s4, v76
	s_movk_i32 s4, 0x78
	s_lshl_b32 s96, s44, 17
	v_cndmask_b32_e32 v3, 0, v3, vcc
	v_cndmask_b32_e32 v2, v2, v4, vcc
	v_cndmask_b32_e32 v5, v10, v11, vcc
	v_cndmask_b32_e32 v4, v12, v13, vcc
	v_lshlrev_b64 v[2:3], 10, v[2:3]
	v_lshl_add_u64 v[2:3], v[4:5], 0, v[2:3]
	v_min_i32_e32 v4, 0x7f, v76
	v_add_u32_e32 v6, 8, v4
	v_ashrrev_i32_e32 v5, 31, v6
	v_cmp_gt_i32_e32 vcc, s4, v76
	s_movk_i32 s4, 0x74
	s_lshl_b32 s0, s57, 8
	v_cndmask_b32_e32 v5, 0, v5, vcc
	v_cndmask_b32_e32 v4, v4, v6, vcc
	v_cndmask_b32_e32 v7, v10, v11, vcc
	v_cndmask_b32_e32 v6, v12, v13, vcc
	v_lshlrev_b64 v[4:5], 10, v[4:5]
	v_lshl_add_u64 v[4:5], v[6:7], 0, v[4:5]
	v_min_i32_e32 v6, 0x7b, v76
	v_add_u32_e32 v8, 12, v6
	v_add_u32_e32 v6, 4, v6
	v_ashrrev_i32_e32 v7, 31, v8
	v_cmp_gt_i32_e32 vcc, s4, v76
	s_movk_i32 s4, 0x70
	v_and_b32_e32 v73, 15, v71
	v_cndmask_b32_e32 v7, 0, v7, vcc
	v_cndmask_b32_e32 v6, v6, v8, vcc
	v_cndmask_b32_e32 v9, v10, v11, vcc
	v_cndmask_b32_e32 v8, v12, v13, vcc
	v_lshlrev_b64 v[6:7], 10, v[6:7]
	v_lshl_add_u64 v[6:7], v[8:9], 0, v[6:7]
	v_min_i32_e32 v8, 0x77, v76
	v_add_u32_e32 v14, 16, v8
	v_add_u32_e32 v8, 8, v8
	v_ashrrev_i32_e32 v9, 31, v14
	v_cmp_gt_i32_e32 vcc, s4, v76
	s_add_u32 s4, s28, s0
	v_lshlrev_b32_e32 v136, 4, v73
	v_cndmask_b32_e32 v9, 0, v9, vcc
	v_cndmask_b32_e32 v8, v8, v14, vcc
	v_cndmask_b32_e32 v11, v10, v11, vcc
	v_cndmask_b32_e32 v10, v12, v13, vcc
	v_lshlrev_b64 v[8:9], 10, v[8:9]
	v_lshl_add_u64 v[8:9], v[10:11], 0, v[8:9]
	s_addc_u32 s5, s29, 0
	v_lshl_add_u64 v[0:1], v[0:1], 0, s[96:97]
	v_lshl_add_u64 v[2:3], v[2:3], 0, s[96:97]
	v_lshl_add_u64 v[4:5], v[4:5], 0, s[96:97]
	v_lshl_add_u64 v[6:7], v[6:7], 0, s[96:97]
	v_lshl_add_u64 v[8:9], v[8:9], 0, s[96:97]
	v_lshl_add_u64 v[10:11], s[4:5], 0, v[136:137]
	s_mul_i32 s96, s44, 0x3000
	v_lshl_add_u64 v[10:11], v[10:11], 0, s[96:97]
	s_mov_b32 s4, 0x784d000
	s_mov_b32 s1, s97
	v_add_co_u32_e32 v12, vcc, s4, v10
	v_lshl_add_u64 v[0:1], v[0:1], 0, s[0:1]
	s_nop 0
	v_addc_co_u32_e32 v13, vcc, 0, v11, vcc
	s_mov_b64 s[4:5], 0x784da00
	v_lshl_add_u64 v[0:1], v[0:1], 0, v[136:137]
	flat_load_dwordx4 v[52:55], v[12:13] offset:2560 nt
	v_lshl_add_u64 v[12:13], v[10:11], 0, s[4:5]
	s_mov_b32 s4, 0x784e000
	flat_load_dwordx4 v[92:95], v[0:1] nt
	flat_load_dwordx4 v[48:51], v[12:13] offset:1536 nt
	flat_load_dwordx4 v[44:47], v[12:13] offset:3072 nt
	v_add_co_u32_e32 v12, vcc, s4, v10
	s_mov_b32 s4, 0x784f000
	s_nop 0
	v_addc_co_u32_e32 v13, vcc, 0, v11, vcc
	flat_load_dwordx4 v[40:43], v[12:13] offset:3072 nt
	v_add_co_u32_e32 v12, vcc, s4, v10
	v_lshl_add_u64 v[2:3], v[2:3], 0, s[0:1]
	s_nop 0
	v_addc_co_u32_e32 v13, vcc, 0, v11, vcc
	flat_load_dwordx4 v[36:39], v[12:13] offset:512 nt
	flat_load_dwordx4 v[28:31], v[12:13] offset:2048 nt
	flat_load_dwordx4 v[24:27], v[12:13] offset:3584 nt
	v_lshl_add_u64 v[14:15], v[2:3], 0, v[136:137]
	v_lshl_add_u64 v[2:3], v[4:5], 0, s[0:1]
	v_lshl_add_u64 v[16:17], v[2:3], 0, v[136:137]
	v_lshl_add_u64 v[2:3], v[6:7], 0, s[0:1]
	v_lshl_add_u64 v[12:13], v[2:3], 0, v[136:137]
	v_lshl_add_u64 v[2:3], v[8:9], 0, s[0:1]
	s_mov_b32 s0, 0x7850000
	v_lshl_add_u64 v[18:19], v[2:3], 0, v[136:137]
	v_add_co_u32_e32 v2, vcc, s0, v10
	s_movk_i32 s0, 0x420
	s_nop 0
	v_addc_co_u32_e32 v3, vcc, 0, v11, vcc
	flat_load_dwordx4 v[20:23], v[2:3] offset:1024 nt
	s_nop 0
	flat_load_dwordx4 v[0:3], v[0:1] offset:512 nt
	s_nop 0
	flat_load_dwordx4 v[64:67], v[14:15] nt
	flat_load_dwordx4 v[4:7], v[14:15] offset:512 nt
	flat_load_dwordx4 v[60:63], v[16:17] nt
	flat_load_dwordx4 v[8:11], v[16:17] offset:512 nt
	flat_load_dwordx4 v[56:59], v[12:13] nt
	s_nop 0
	flat_load_dwordx4 v[12:15], v[12:13] offset:512 nt
	s_nop 0
	flat_load_dwordx4 v[32:35], v[18:19] nt
	s_nop 0
	flat_load_dwordx4 v[16:19], v[18:19] offset:512 nt
	v_mad_u32_u24 v74, v73, s0, 16
	s_movk_i32 s0, 0x88
	v_cmp_gt_u32_e64 s[10:11], 8, v73
	v_and_b32_e32 v72, 7, v71
	v_cmp_gt_i32_e64 s[24:25], s0, v76
	v_cmp_eq_u32_e32 vcc, 7, v72
	v_cmp_eq_u32_e64 s[12:13], 6, v72
	v_cmp_eq_u32_e64 s[14:15], 5, v72
	v_cmp_eq_u32_e64 s[16:17], 4, v72
	v_cmp_eq_u32_e64 s[18:19], 3, v72
	v_cmp_eq_u32_e64 s[20:21], 2, v72
	v_cmp_eq_u32_e64 s[22:23], 1, v72
	v_or_b32_e32 v72, 0x80, v73
	s_and_b64 s[0:1], s[10:11], s[24:25]
	v_lshl_add_u32 v74, v76, 2, v74
	s_waitcnt lgkmcnt(0)
	s_barrier
	s_waitcnt vmcnt(0)
	v_mul_f32_e32 v77, v93, v53
	v_mul_f32_e32 v79, v93, v49
	v_mul_f32_e32 v81, v93, v45
	v_fmac_f32_e32 v77, v92, v52
	v_fmac_f32_e32 v79, v92, v48
	v_fmac_f32_e32 v81, v92, v44
	v_fmac_f32_e32 v77, v94, v54
	v_mul_f32_e32 v83, v93, v41
	v_fmac_f32_e32 v83, v92, v40
	v_fmac_f32_e32 v79, v94, v50
	v_fmac_f32_e32 v81, v94, v46
	v_fmac_f32_e32 v83, v94, v42
	v_mul_f32_e32 v85, v93, v37
	v_mul_f32_e32 v87, v93, v29
	v_mul_f32_e32 v89, v93, v25
	v_fmac_f32_e32 v85, v92, v36
	v_fmac_f32_e32 v87, v92, v28
	v_fmac_f32_e32 v89, v92, v24
	v_fmac_f32_e32 v85, v94, v38
	v_mul_f32_e32 v91, v93, v21
	v_fmac_f32_e32 v91, v92, v20
	v_fmac_f32_e32 v87, v94, v30
	v_fmac_f32_e32 v89, v94, v26
	v_fmac_f32_e32 v91, v94, v22
	v_fmac_f32_e32 v77, v95, v55
	v_fmac_f32_e32 v79, v95, v51
	v_fmac_f32_e32 v81, v95, v47
	v_fmac_f32_e32 v83, v95, v43
	v_fmac_f32_e32 v85, v95, v39
	v_fmac_f32_e32 v87, v95, v31
	v_fmac_f32_e32 v89, v95, v27
	v_fmac_f32_e32 v91, v95, v23
	v_add_f32_dpp v77, v77, v77 quad_perm:[1,0,3,2] row_mask:0xf bank_mask:0xf bound_ctrl:1
	v_add_f32_dpp v79, v79, v79 quad_perm:[1,0,3,2] row_mask:0xf bank_mask:0xf bound_ctrl:1
	v_add_f32_dpp v81, v81, v81 quad_perm:[1,0,3,2] row_mask:0xf bank_mask:0xf bound_ctrl:1
	v_add_f32_dpp v83, v83, v83 quad_perm:[1,0,3,2] row_mask:0xf bank_mask:0xf bound_ctrl:1
	v_add_f32_dpp v85, v85, v85 quad_perm:[1,0,3,2] row_mask:0xf bank_mask:0xf bound_ctrl:1
	v_add_f32_dpp v87, v87, v87 quad_perm:[1,0,3,2] row_mask:0xf bank_mask:0xf bound_ctrl:1
	v_add_f32_dpp v89, v89, v89 quad_perm:[1,0,3,2] row_mask:0xf bank_mask:0xf bound_ctrl:1
	v_add_f32_dpp v91, v91, v91 quad_perm:[1,0,3,2] row_mask:0xf bank_mask:0xf bound_ctrl:1
	v_add_f32_dpp v77, v77, v77 quad_perm:[2,3,0,1] row_mask:0xf bank_mask:0xf bound_ctrl:1
	v_add_f32_dpp v79, v79, v79 quad_perm:[2,3,0,1] row_mask:0xf bank_mask:0xf bound_ctrl:1
	v_add_f32_dpp v81, v81, v81 quad_perm:[2,3,0,1] row_mask:0xf bank_mask:0xf bound_ctrl:1
	v_add_f32_dpp v83, v83, v83 quad_perm:[2,3,0,1] row_mask:0xf bank_mask:0xf bound_ctrl:1
	v_add_f32_dpp v85, v85, v85 quad_perm:[2,3,0,1] row_mask:0xf bank_mask:0xf bound_ctrl:1
	v_add_f32_dpp v87, v87, v87 quad_perm:[2,3,0,1] row_mask:0xf bank_mask:0xf bound_ctrl:1
	v_add_f32_dpp v89, v89, v89 quad_perm:[2,3,0,1] row_mask:0xf bank_mask:0xf bound_ctrl:1
	v_add_f32_dpp v91, v91, v91 quad_perm:[2,3,0,1] row_mask:0xf bank_mask:0xf bound_ctrl:1
	v_add_f32_dpp v77, v77, v77 row_ror:4 row_mask:0xf bank_mask:0xf bound_ctrl:1
	v_add_f32_dpp v79, v79, v79 row_ror:4 row_mask:0xf bank_mask:0xf bound_ctrl:1
	v_add_f32_dpp v81, v81, v81 row_ror:4 row_mask:0xf bank_mask:0xf bound_ctrl:1
	v_add_f32_dpp v83, v83, v83 row_ror:4 row_mask:0xf bank_mask:0xf bound_ctrl:1
	v_add_f32_dpp v85, v85, v85 row_ror:4 row_mask:0xf bank_mask:0xf bound_ctrl:1
	v_add_f32_dpp v87, v87, v87 row_ror:4 row_mask:0xf bank_mask:0xf bound_ctrl:1
	v_add_f32_dpp v89, v89, v89 row_ror:4 row_mask:0xf bank_mask:0xf bound_ctrl:1
	v_add_f32_dpp v91, v91, v91 row_ror:4 row_mask:0xf bank_mask:0xf bound_ctrl:1
	v_mov_b32_dpp v78, v77 row_ror:8 row_mask:0xf bank_mask:0xf bound_ctrl:1
	v_mov_b32_dpp v80, v79 row_ror:8 row_mask:0xf bank_mask:0xf bound_ctrl:1
	v_mov_b32_dpp v82, v81 row_ror:8 row_mask:0xf bank_mask:0xf bound_ctrl:1
	v_mov_b32_dpp v84, v83 row_ror:8 row_mask:0xf bank_mask:0xf bound_ctrl:1
	v_mov_b32_dpp v86, v85 row_ror:8 row_mask:0xf bank_mask:0xf bound_ctrl:1
	v_mov_b32_dpp v88, v87 row_ror:8 row_mask:0xf bank_mask:0xf bound_ctrl:1
	v_mov_b32_dpp v90, v89 row_ror:8 row_mask:0xf bank_mask:0xf bound_ctrl:1
	v_mov_b32_dpp v92, v91 row_ror:8 row_mask:0xf bank_mask:0xf bound_ctrl:1
	s_and_saveexec_b64 s[6:7], s[0:1]
	s_cbranch_execz .LBB0_923
	v_add_f32_e32 v79, v79, v80
	v_add_f32_e32 v77, v77, v78
	v_add_f32_e32 v81, v81, v82
	v_cndmask_b32_e64 v77, v77, v79, s[22:23]
	v_add_f32_e32 v83, v83, v84
	v_cndmask_b32_e64 v77, v77, v81, s[20:21]
	v_add_f32_e32 v85, v85, v86
	v_cndmask_b32_e64 v77, v77, v83, s[18:19]
	v_add_f32_e32 v87, v87, v88
	v_cndmask_b32_e64 v77, v77, v85, s[16:17]
	v_add_f32_e32 v89, v89, v90
	v_cndmask_b32_e64 v77, v77, v87, s[14:15]
	v_add_f32_e32 v91, v91, v92
	v_cndmask_b32_e64 v77, v77, v89, s[12:13]
	v_cmp_lt_i32_e64 s[0:1], v76, v73
	v_cmp_gt_i32_e64 s[4:5], v76, v72
	v_cndmask_b32_e32 v77, v77, v91, vcc
	s_or_b64 s[0:1], s[0:1], s[4:5]
	v_cndmask_b32_e64 v76, v77, v215, s[0:1]
	ds_write_b32 v74, v76
